# mixer A QK: q-fragment waits vmcnt 11/10/9/8 -> 15/14/13/12 (no longer waits on the just-issued staging loads)
# speedup vs baseline: 1.0168x; 1.0030x over previous
; #define LAS __attribute__((address_space(3)))
; #define MFMA32(a, b, c) __builtin_amdgcn_mfma_f32_32x32x16_bf16((a), (b), (c), 0, 0, 0)
; #define A_LOADQ(SB) do { if (active) { int pb, i0, rbq; A_QPOS(SB, pb, i0, rbq); const bf16* qr = Qg + (size_t)(pb + i0 + ql) * 64 + 8 * hh; \
;                 _Pragma("unroll") for (int s = 0; s < 4; ++s) qf[s] = *(const bf16x8*)(qr + 16 * s); } } while (0)
; __device__ __forceinline__ void attnA_unit(LAS unsigned char* lds, const Args& A, int unit) {
;     ...
;                 for (int s = 0; s < 4; ++s)
; #pragma unroll
;                     for (int kt = 0; kt < 5; ++kt) S[kt] = MFMA32(*(const LAS bf16x8*)(kt_l + (rb + 32 * kt + ql) * AST + hh * 16 + 32 * s), qf[s], S[kt]);
;                 asm volatile("" : "+v"(S[4][15]));
;                 if (sb + 1 < nsb) { A_LOADQ(sb + 1); }
.LBB0_295:
	v_add_u32_e32 v0, v163, v144
	v_mad_u64_u32 v[170:171], s[22:23], v0, s88, v[148:149]
	ds_read_b128 v[0:3], v170 offset:4096
	ds_read_b128 v[166:169], v170 offset:4128
	s_andn2_b64 vcc, exec, s[82:83]
	s_waitcnt vmcnt(15) lgkmcnt(1)
	v_mfma_f32_32x32x16_bf16 v[64:79], v[0:3], v[80:83], 0
	ds_read_b128 v[0:3], v170 offset:8704
	s_waitcnt vmcnt(14) lgkmcnt(1)
	v_mfma_f32_32x32x16_bf16 v[64:79], v[166:169], v[84:87], v[64:79]
	ds_read_b128 v[166:169], v170 offset:8736
	s_waitcnt lgkmcnt(1)
	v_mfma_f32_32x32x16_bf16 v[48:63], v[0:3], v[80:83], 0
	ds_read_b128 v[0:3], v170 offset:13312
	s_waitcnt lgkmcnt(1)
	v_mfma_f32_32x32x16_bf16 v[48:63], v[166:169], v[84:87], v[48:63]
	ds_read_b128 v[166:169], v170 offset:13344
	s_waitcnt lgkmcnt(1)
	v_mfma_f32_32x32x16_bf16 v[32:47], v[0:3], v[80:83], 0
	ds_read_b128 v[0:3], v170 offset:17920
	s_waitcnt lgkmcnt(1)
	v_mfma_f32_32x32x16_bf16 v[32:47], v[166:169], v[84:87], v[32:47]
	ds_read_b128 v[166:169], v170 offset:17952
	s_waitcnt lgkmcnt(1)
	v_mfma_f32_32x32x16_bf16 v[16:31], v[0:3], v[80:83], 0
	ds_read_b128 v[0:3], v170 offset:22528
	s_waitcnt lgkmcnt(1)
	v_mfma_f32_32x32x16_bf16 v[16:31], v[166:169], v[84:87], v[16:31]
	ds_read_b128 v[166:169], v170 offset:22560
	s_waitcnt lgkmcnt(1)
	v_mfma_f32_32x32x16_bf16 v[0:15], v[0:3], v[80:83], 0
	s_waitcnt lgkmcnt(0)
	v_mfma_f32_32x32x16_bf16 v[0:15], v[166:169], v[84:87], v[0:15]
	ds_read_b128 v[166:169], v170 offset:4160
	ds_read_b128 v[172:175], v170 offset:8768
	s_waitcnt vmcnt(13) lgkmcnt(1)
	v_mfma_f32_32x32x16_bf16 v[64:79], v[166:169], v[88:91], v[64:79]
	ds_read_b128 v[166:169], v170 offset:13376
	s_waitcnt lgkmcnt(1)
	v_mfma_f32_32x32x16_bf16 v[48:63], v[172:175], v[88:91], v[48:63]
	ds_read_b128 v[172:175], v170 offset:17984
	s_waitcnt lgkmcnt(1)
	v_mfma_f32_32x32x16_bf16 v[32:47], v[166:169], v[88:91], v[32:47]
	ds_read_b128 v[166:169], v170 offset:22592
	s_waitcnt lgkmcnt(1)
	v_mfma_f32_32x32x16_bf16 v[16:31], v[172:175], v[88:91], v[16:31]
	ds_read_b128 v[172:175], v170 offset:4192
	s_waitcnt lgkmcnt(1)
	v_mfma_f32_32x32x16_bf16 v[0:15], v[166:169], v[88:91], v[0:15]
	ds_read_b128 v[166:169], v170 offset:8800
	s_waitcnt vmcnt(12) lgkmcnt(1)
	v_mfma_f32_32x32x16_bf16 v[64:79], v[172:175], v[92:95], v[64:79]
	ds_read_b128 v[172:175], v170 offset:13408
	s_waitcnt lgkmcnt(1)
	v_mfma_f32_32x32x16_bf16 v[48:63], v[166:169], v[92:95], v[48:63]
	ds_read_b128 v[166:169], v170 offset:22624
	s_waitcnt lgkmcnt(1)
	v_mfma_f32_32x32x16_bf16 v[32:47], v[172:175], v[92:95], v[32:47]
	ds_read_b128 v[172:175], v170 offset:18016
	s_waitcnt lgkmcnt(1)
	v_mfma_f32_32x32x16_bf16 v[0:15], v[166:169], v[92:95], v[0:15]
	s_waitcnt lgkmcnt(0)
	v_mfma_f32_32x32x16_bf16 v[16:31], v[172:175], v[92:95], v[16:31]
	s_cbranch_vccnz .LBB0_301
	s_and_b64 vcc, exec, s[42:43]
	s_cbranch_vccz .LBB0_298
	s_and_b64 s[22:23], s[76:77], exec
	s_cselect_b32 s24, 0, s97
	s_add_i32 s25, s90, 0x100
	s_and_b64 s[22:23], s[76:77], exec
	s_cselect_b32 s22, s25, s91
	v_add_u32_e32 v80, s22, v155
	v_mov_b32_e32 v81, s24
	s_cbranch_execz .LBB0_299
	s_branch .LBB0_300
